# P6 start policy: every second non-scan workgroup starts on prompt attention (was every third); on top of v11
# speedup vs baseline: 1.0182x; 1.0024x over previous
; __global__ void __launch_bounds__(NWAVES * 64, 2) mega_fwd(Args args) {
;     ...
;     const bool a_first = (vcu >= NB * NH) && (vcu % 3 == 0);
;     if (!a_first) p_attn_sample(P, in[2], in[3], in[6], HEADS, (const float*)(ws + WS_SB), (unsigned*)(ctl + 256), MISC + 17, wave, lane);
.LBB0_1239:
	v_readlane_b32 s0, v244, 0
	s_cmp_gt_i32 s0, 63
	s_mov_b64 s[20:21], 0
	v_readlane_b32 s1, v244, 1
	s_cbranch_scc0 .LBB0_1241
	s_and_b32 s0, s0, 1
	s_cmp_eq_u32 s0, 0
	s_cselect_b64 s[20:21], -1, 0
